# S5 table construction deferred from the prologue into the In0 tail (idle workgroups), layer-1 and Wdn0 weight transposes moved to a second deferral site in the Up0 tail, on top of v15
# speedup vs baseline: 1.0033x; 1.0033x over previous
; DI unsigned pk2(float lo, float hi) { unsigned r; asm volatile("v_cvt_pk_bf16_f32 %0, %1, %2" : "=v"(r) : "v"(lo), "v"(hi)); return r; }
; DI float bflo(unsigned u) { return __uint_as_float(u << 16); }
; DI float bfhi(unsigned u) { return __uint_as_float(u & 0xffff0000u); }
; DI void phase_prologue(const Prm& p, LAS unsigned char* lds, int tid, int lane, int wave) {
;     ...
;     for (int row = gw; row < NT; row += NGW) {
;         const float* src;
;         if (row < NTP) { const int b = row / TP, t = row - b * TP; src = t < 16 ? p.meta + (size_t)t * 1024 : p.x_prompt + ((size_t)b * 4096 + (t - 16)) * 1024; }
;         else src = p.x_sample + (size_t)(row - NTP) * 1024;
;         float ss = 0.f;
; #pragma unroll
;         for (int j = 0; j < 4; ++j) { const f32x4 v = ((const f32x4*)src)[lane + 64 * j]; u32x2 o; o.x = pk2(v.x, v.y); o.y = pk2(v.z, v.w);
;             const float a0 = bflo(o.x), a1 = bfhi(o.x), a2 = bflo(o.y), a3 = bfhi(o.y); ss += (a0 * a0 + a1 * a1) + (a2 * a2 + a3 * a3);
;             ((u32x2*)(p.XB + (size_t)row * 1024))[lane + 64 * j] = o; }
.LBB0_76:
	s_cmp_eq_u32 s98, 1
	s_cbranch_scc1 .Ls5_entry
	s_cmp_eq_u32 s98, 2
	s_cbranch_scc1 .Ltr_tramp_b
	s_load_dwordx16 s[36:51], s[0:1], 0x0
	v_lshlrev_b32_e32 v2, 2, v152
	v_lshlrev_b32_e32 v156, 3, v152
	s_waitcnt lgkmcnt(0)
	v_writelane_b32 v254, s36, 54
	s_nop 1
	v_writelane_b32 v254, s37, 55
	v_writelane_b32 v254, s38, 56
	v_writelane_b32 v254, s39, 57
	v_writelane_b32 v254, s40, 58
	v_writelane_b32 v254, s41, 59
	v_writelane_b32 v254, s42, 60
	v_writelane_b32 v255, s46, 0
	v_writelane_b32 v254, s43, 61
	v_writelane_b32 v255, s47, 1
	v_writelane_b32 v254, s44, 62
	v_writelane_b32 v255, s48, 2
	v_writelane_b32 v254, s45, 63
	v_writelane_b32 v255, s49, 3
	v_writelane_b32 v255, s50, 4
	v_readlane_b32 s2, v254, 52
	v_writelane_b32 v255, s51, 5
	s_cmp_gt_i32 s2, 0x827f
	v_readlane_b32 s3, v254, 53
	s_cbranch_scc1 .LBB0_90
	s_load_dwordx4 s[36:39], s[0:1], 0x140
	v_readlane_b32 s8, v254, 52
	s_mov_b32 s28, s8
	s_ashr_i32 s29, s28, 31
	s_add_i32 s8, s8, 0xffff7f80
	s_lshl_b64 s[24:25], s[28:29], 2
	s_waitcnt lgkmcnt(0)
	s_add_u32 s24, s36, s24
	s_addc_u32 s25, s37, s25
	s_load_dwordx16 s[36:51], s[0:1], 0x100
	v_readlane_b32 s26, v254, 50
	v_readlane_b32 s27, v254, 51
	s_mov_b32 s30, s26
	s_ashr_i32 s31, s26, 31
	s_lshl_b64 s[26:27], s[30:31], 2
	s_lshl_b64 s[34:35], s[28:29], 6
	s_waitcnt lgkmcnt(0)
	s_add_u32 s34, s50, s34
	v_mov_b32_e32 v3, 0
	s_addc_u32 s35, s51, s35
	s_mov_b32 s7, 0
	v_lshl_add_u64 v[4:5], s[34:35], 0, v[2:3]
	s_lshl_b64 s[36:37], s[30:31], 6
	s_mov_b32 s6, s28
	s_lshl_b64 s[34:35], s[28:29], 11
	v_readlane_b32 s9, v254, 53
	v_writelane_b32 v254, s6, 52
	s_add_u32 s34, s48, s34
	v_mbcnt_lo_u32_b32 v8, -1, 0
	v_writelane_b32 v254, s7, 53
	v_mov_b32_e32 v157, v3
	s_addc_u32 s35, s49, s35
	s_mov_b32 s6, s30
	v_mbcnt_hi_u32_b32 v8, -1, v8
	v_lshl_add_u64 v[6:7], s[34:35], 0, v[156:157]
	s_mov_b64 s[34:35], 0x400
	v_writelane_b32 v254, s6, 50
	v_and_b32_e32 v9, 64, v8
	v_cmp_gt_u32_e64 s[2:3], 16, v152
	v_cmp_eq_u32_e64 s[4:5], 0, v152
	v_lshl_add_u64 v[6:7], v[6:7], 0, s[34:35]
	v_writelane_b32 v254, s7, 51
	s_lshl_b64 s[38:39], s[30:31], 11
	v_lshlrev_b32_e32 v1, 4, v152
	v_add_u32_e32 v9, 64, v9
	v_xor_b32_e32 v10, 1, v8
	v_xor_b32_e32 v11, 2, v8
	v_xor_b32_e32 v12, 4, v8
	v_xor_b32_e32 v13, 8, v8
	v_xor_b32_e32 v14, 16, v8
	v_xor_b32_e32 v15, 32, v8
	v_mov_b32_e32 v16, 0x358637bd
	s_load_dwordx2 s[48:49], s[0:1], 0x0
	s_load_dwordx2 s[50:51], s[0:1], 0x8
	s_load_dwordx2 s[52:53], s[0:1], 0x38
	v_readlane_b32 s54, v254, 50
	s_mov_b32 s55, 1
	s_add_i32 s6, s8, 0x8080
	s_waitcnt lgkmcnt(0)
	s_mul_hi_u32 s40, s6, 0xff011
	s_mul_i32 s41, s40, 0x1010
	s_sub_i32 s41, s6, s41
	s_sub_i32 s42, s41, 16
	s_lshl_b32 s43, s40, 12
	s_add_i32 s42, s42, s43
	s_cmp_lt_i32 s41, 16
	s_cselect_b32 s42, s41, s42
	s_cselect_b32 s34, s52, s48
	s_cselect_b32 s35, s53, s49
	s_sub_i32 s43, s6, 0x8080
	s_cmp_gt_i32 s6, 0x807f
	s_cselect_b32 s42, s43, s42
	s_cselect_b32 s34, s50, s34
	s_cselect_b32 s35, s51, s35
	s_mov_b32 s43, 0
	s_lshl_b64 s[42:43], s[42:43], 12
	s_add_u32 s34, s34, s42
	s_addc_u32 s35, s35, s43
	global_load_dwordx4 v[102:105], v1, s[34:35]
	global_load_dwordx4 v[106:109], v1, s[34:35] offset:1024
	global_load_dwordx4 v[110:113], v1, s[34:35] offset:2048
	global_load_dwordx4 v[114:117], v1, s[34:35] offset:3072

; #define LAS __attribute__((address_space(3)))
; DI void phase_prologue(const Prm& p, LAS unsigned char* lds, int tid, int lane, int wave) {
;     ...
;     {
;         LAS float* zr_ = (LAS float*)lds; LAS float* zi_ = zr_ + 64; LAS float* wr_ = zi_ + 64; LAS float* wi_ = wr_ + 64;
;         LAS float* bbr = wi_ + 64; LAS float* bbi = bbr + 1024; LAS float* cwr = bbi + 1024; LAS float* cwi = cwr + 16 * 65;
;         for (int pair = blockIdx.x; pair < 512; pair += gridDim.x) { const int g = pair >> 4, tau = pair & 15;
.Ls5_go:
	s_cmpk_gt_i32 s84, 0x1ff
	v_lshrrev_b32_e32 v157, 4, v154
	v_and_b32_e32 v160, 15, v154
	s_waitcnt lgkmcnt(0)
	s_barrier
	s_cbranch_scc1 .LBB0_105
	s_cmp_eq_u32 s98, 0
	s_cbranch_scc1 .LBB0_105
	v_add_u32_e32 v7, 0x200, v154
	v_mul_u32_u24_e32 v10, 0x41, v157
	v_lshrrev_b32_e32 v5, 6, v154
	v_lshrrev_b32_e32 v6, 2, v7
	v_lshrrev_b32_e32 v7, 6, v7
	v_lshl_add_u32 v3, v152, 2, 0
	s_movk_i32 s4, 0x100
	v_mul_u32_u24_e32 v5, 0x41, v5
	v_and_b32_e32 v6, 0x1fc, v6
	v_mul_u32_u24_e32 v7, 0x41, v7
	v_lshl_add_u32 v9, v160, 2, 0
	v_lshl_add_u32 v10, v10, 2, 0
	v_cmp_gt_u32_e64 s[2:3], 64, v154
	v_lshl_add_u32 v1, v154, 2, 0
	v_cmp_gt_u32_e64 s[4:5], s4, v154
	v_cmp_eq_u32_e64 s[6:7], v157, v160
	v_lshl_add_u32 v4, v157, 2, 0
	v_lshl_add_u32 v5, v5, 2, v3
	v_add_u32_e32 v6, 0, v6
	v_lshl_add_u32 v7, v7, 2, v3
	v_mov_b32_e32 v8, 0
	v_add_u32_e32 v9, 0x400, v9
	v_add_u32_e32 v10, 0x2400, v10
	s_mov_b32 s29, s84
	s_branch .LBB0_98

; DI unsigned pk2(float lo, float hi) { unsigned r; asm volatile("v_cvt_pk_bf16_f32 %0, %1, %2" : "=v"(r) : "v"(lo), "v"(hi)); return r; }
; DI void phase_prologue(const Prm& p, LAS unsigned char* lds, int tid, int lane, int wave) {
;     ...
;     for (int i = gtid; i < 32 * 256 * 64; i += GT) {
;         const int g = i >> 14, t = (i >> 10) & 15, pch = (i >> 6) & 15, n = i & 63; float wr_, wi_; s5_pow(p, g, n, (float)(t + 1), wr_, wi_);
;         const float cr = p.c_re[(g * 16 + pch) * 64 + n], ci = p.c_im[(g * 16 + pch) * 64 + n];
;         *(unsigned*)(p.TG + 131072 + ((size_t)(g * 256 + t * 16 + pch)) * 128 + 2 * n) = pk2(cr * wr_ - ci * wi_, -(cr * wi_ + ci * wr_)); }
.LBB0_105:
	s_mov_b32 s2, 0x80000
	s_lshl_b32 s8, s88, 9
	v_cmp_gt_i32_e32 vcc, s2, v162
	s_and_saveexec_b64 s[4:5], vcc
	s_cbranch_execz .LBB0_110
	s_cmp_eq_u32 s98, 0
	s_cbranch_scc1 .LBB0_110
	v_mov_b32_e32 v3, 0
	v_lshl_add_u64 v[2:3], s[36:37], 0, v[2:3]
	s_mov_b64 s[2:3], 0x40000
	v_lshl_add_u64 v[2:3], v[2:3], 0, s[2:3]
	s_mov_b64 s[2:3], 0
	v_mov_b32_e32 v1, v162
	s_mov_b32 s6, 0x7ffff

; DI void phase_prologue(const Prm& p, LAS unsigned char* lds, int tid, int lane, int wave) {
;     ...
;     if (gtid < 2048) { float wr_, wi_; s5_pow(p, gtid >> 6, gtid & 63, 16.f, wr_, wi_); p.A16[2 * gtid] = wr_; p.A16[2 * gtid + 1] = wi_; }
; DI void xcd_barrier(const XcdBarrier& b) {
;     asm volatile("s_waitcnt vmcnt(0)" ::: "memory");
;     __syncthreads();
;     if (threadIdx.x == 0) {
;         unsigned* bar = b.bar;
;         __builtin_amdgcn_s_waitcnt(0);
;         unsigned nloc = b.st[0], nx = b.st[1];
;         if (nloc == 0u) { xcd_barrier_complete(bar, b.x, nloc, nx); b.st[0] = nloc; b.st[1] = nx; }
.LBB0_110:
	v_writelane_b32 v255, s8, 6
	s_nop 1
	v_writelane_b32 v255, s9, 7
	s_or_b64 exec, exec, s[4:5]
	s_load_dwordx16 s[16:31], s[0:1], 0x198
	s_movk_i32 s0, 0x800
	v_cmp_gt_i32_e32 vcc, s0, v162
	s_waitcnt lgkmcnt(0)
	v_writelane_b32 v255, s16, 8
	s_nop 1
	v_writelane_b32 v255, s17, 9
	v_writelane_b32 v255, s18, 10
	v_writelane_b32 v255, s19, 11
	v_writelane_b32 v255, s20, 12
	v_writelane_b32 v255, s21, 13
	v_writelane_b32 v255, s22, 14
	v_writelane_b32 v255, s23, 15
	v_writelane_b32 v255, s24, 16
	v_writelane_b32 v255, s25, 17
	v_writelane_b32 v255, s26, 18
	v_writelane_b32 v255, s27, 19
	v_writelane_b32 v255, s28, 20
	v_writelane_b32 v255, s29, 21
	v_writelane_b32 v255, s30, 22
	v_writelane_b32 v255, s31, 23
	s_and_saveexec_b64 s[0:1], vcc
	s_cbranch_execz .LBB0_112
	s_cmp_eq_u32 s98, 0
	s_cbranch_scc1 .LBB0_112
	v_ashrrev_i32_e32 v2, 6, v162
	v_ashrrev_i32_e32 v3, 31, v2
	v_lshl_add_u64 v[2:3], v[2:3], 2, s[12:13]
	global_load_dword v1, v[2:3], off
	v_lshlrev_b64 v[2:3], 2, v[162:163]
	v_lshl_add_u64 v[4:5], s[80:81], 0, v[2:3]
	v_lshl_add_u64 v[2:3], s[82:83], 0, v[2:3]
	global_load_dword v4, v[4:5], off
	s_nop 0
	global_load_dword v2, v[2:3], off
	v_lshlrev_b32_e32 v6, 1, v162
	v_ashrrev_i32_e32 v7, 31, v6
	v_lshl_add_u64 v[6:7], v[6:7], 2, s[40:41]
	s_waitcnt vmcnt(2)
	v_mul_f32_e32 v1, 0x3fb8aa3b, v1
	v_exp_f32_e32 v1, v1
	s_nop 0
	v_mul_f32_e32 v1, 0x41800000, v1
	s_waitcnt vmcnt(1)
	v_mul_f32_e32 v3, v4, v1
	s_waitcnt vmcnt(0)
	v_mul_f32_e32 v1, v2, v1
	v_mul_f32_e32 v2, 0x3fb8aa3b, v3
	v_mul_f32_e32 v3, 0.15915494, v1
	v_rndne_f32_e32 v3, v3
	v_fma_f32 v1, v1, 0.15915494, -v3
	v_exp_f32_e32 v2, v2
	v_cos_f32_e32 v4, v1
	v_sin_f32_e32 v5, v1
	s_nop 0
	v_pk_mul_f32 v[2:3], v[2:3], v[4:5] op_sel_hi:[0,1]
	global_store_dwordx2 v[6:7], v[2:3], off
.LBB0_112:
	s_or_b64 exec, exec, s[0:1]
	s_cmp_eq_u32 s98, 1
	s_cbranch_scc1 .Ls5_ret
	s_waitcnt vmcnt(0)
	s_barrier
	s_mov_b64 s[0:1], exec
	v_readlane_b32 s2, v254, 10
	v_readlane_b32 s3, v254, 11
	s_and_b64 s[2:3], s[0:1], s[2:3]
	s_mov_b64 exec, s[2:3]
	s_cbranch_execz .LBB0_164
	s_add_i32 s2, 0, 0x20000
	v_mov_b32_e32 v1, s2
	s_waitcnt vmcnt(0) expcnt(0) lgkmcnt(0)
	ds_read_b32 v3, v1
	s_add_i32 s2, 0, 0x20004
	v_mov_b32_e32 v1, s2
	ds_read_b32 v2, v1
	s_waitcnt lgkmcnt(1)
	v_cmp_ne_u32_e32 vcc, 0, v3
	s_cbranch_vccnz .LBB0_128
	v_readlane_b32 s2, v254, 8
	s_mul_i32 s18, s89, s2
	s_add_u32 s2, s94, 0x1000
	s_addc_u32 s3, s95, 0
	s_add_u32 s4, s94, 0x1100
	s_addc_u32 s5, s95, 0
	s_add_u32 s6, s94, 0x1200
	s_addc_u32 s7, s95, 0
	s_add_u32 s8, s94, 0x1300
	s_mul_i32 s18, s18, s88
	s_addc_u32 s9, s95, 0
	s_mov_b32 s19, 1
	v_mov_b32_e32 v17, 0
	s_branch .LBB0_116

; #define LAS __attribute__((address_space(3)))
; DI void phase_prologue(const Prm& p, LAS unsigned char* lds, int tid, int lane, int wave) {
;     ...
;     for (int it = gw; it < NITEMS; it += NGW) {
;         int r = it;
;         if (r < I1) { transpose_item(p.w_in_even, 2560, p.Wt1, 1024, p.ln_mix, scr, r, lane); continue; } r -= I1;
;         if (r < I2) { transpose_item(p.w_glu, 512, p.Wglu, 512, nullptr, scr, r, lane); continue; } r -= I2;
;         if (r < I3) { transpose_item(p.w_out_even, 1024, p.Wo0, 1024, nullptr, scr, r, lane); continue; } r -= I3;
;         if (r < I4) { transpose_item(p.w_up, 4096, p.Wup0, 1024, p.ln_mlp, scr, r, lane); continue; } r -= I4;
;         if (r < I5) { transpose_item(p.w_down, 1024, p.Wdn0, 4096, nullptr, scr, r, lane); continue; } r -= I5;
;         if (r < I6) { transpose_item(p.w_in_odd, 3072, p.Wqkv, 1024, p.ln_mix + 1024, scr, r, lane); continue; } r -= I6;
;         if (r < I3) { transpose_item(p.w_out_odd, 1024, p.Wo1, 1024, nullptr, scr, r, lane); continue; } r -= I3;
;         if (r < I4) { transpose_item(p.w_up + (size_t)1024 * 4096, 4096, p.Wup1, 1024, p.ln_mlp + 1024, scr, r, lane); continue; } r -= I4;
;         transpose_item(p.w_down + (size_t)4096 * 1024, 1024, p.Wdn1, 4096, nullptr, scr, r, lane);
;     }
;     ...
;     {
;         LAS float* zr_ = (LAS float*)lds; LAS float* zi_ = zr_ + 64; LAS float* wr_ = zi_ + 64; LAS float* wi_ = wr_ + 64;
;         LAS float* bbr = wi_ + 64; LAS float* bbi = bbr + 1024; LAS float* cwr = bbi + 1024; LAS float* cwi = cwr + 16 * 65;
;         for (int pair = blockIdx.x; pair < 512; pair += gridDim.x) { const int g = pair >> 4, tau = pair & 15;
.Ltr_mod_done:
	s_cmp_lt_u32 s84, s4
	s_cbranch_scc1 .Ltr_skip
	s_sub_u32 s5, s88, s4
	v_mov_b32_e32 v200, v1
	v_mov_b32_e32 v201, v2
	v_mov_b32_e32 v202, v3
	v_mov_b32_e32 v203, v4
	v_mov_b32_e32 v204, v5
	v_mov_b32_e32 v205, v6
	v_mov_b32_e32 v206, v7
	v_mov_b32_e32 v207, v8
	v_mov_b32_e32 v208, v9
	v_mov_b32_e32 v209, v10
	v_mov_b32_e32 v210, v11
	v_mov_b32_e32 v211, v14
	v_mov_b32_e32 v212, v15
	v_mov_b32_e32 v213, v19
	v_mov_b32_e32 v214, v70
	v_mov_b32_e32 v215, v71
	v_mov_b32_e32 v216, v75
	v_mov_b32_e32 v217, v80
	v_mov_b32_e32 v218, v81
	v_mov_b32_e32 v219, v82
	v_mov_b32_e32 v220, v83
	v_writelane_b32 v253, s26, 0
	v_writelane_b32 v253, s27, 1
	v_writelane_b32 v253, s34, 2
	v_writelane_b32 v253, s36, 3
	v_writelane_b32 v253, s37, 4
	v_writelane_b32 v253, s38, 5
	v_writelane_b32 v253, s39, 6
	v_writelane_b32 v253, s40, 7
	v_writelane_b32 v253, s41, 8
	v_writelane_b32 v253, s42, 9
	v_writelane_b32 v253, s43, 10
	v_writelane_b32 v253, s44, 11
	v_writelane_b32 v253, s45, 12
	v_writelane_b32 v253, s46, 13
	v_writelane_b32 v253, s47, 14
	v_writelane_b32 v253, s48, 15
	v_writelane_b32 v253, s49, 16
	v_writelane_b32 v253, s50, 17
	v_writelane_b32 v253, s51, 18
	v_writelane_b32 v253, s53, 19
	v_writelane_b32 v253, s88, 20
	v_writelane_b32 v253, s12, 21
	v_writelane_b32 v253, s13, 22
	v_writelane_b32 v253, s14, 23
	v_writelane_b32 v253, s15, 24
	v_writelane_b32 v253, s16, 25
	v_writelane_b32 v253, s17, 26
	v_writelane_b32 v253, s18, 27
	v_writelane_b32 v253, s19, 28
	v_writelane_b32 v253, s20, 29
	v_writelane_b32 v253, s21, 30
	v_writelane_b32 v253, s22, 31
	v_writelane_b32 v253, s23, 32
	v_writelane_b32 v253, s4, 40
	v_writelane_b32 v253, s84, 44
	s_mov_b64 s[0:1], s[100:101]
	s_load_dwordx8 s[68:75], s[0:1], 0x40
	s_load_dwordx4 s[24:27], s[0:1], 0xb0
	v_readlane_b32 s96, v254, 50
	v_readlane_b32 s97, v254, 52
	v_readlane_b32 s3, v254, 49
	s_sub_u32 s2, s84, s4
	s_lshl_b32 s2, s2, 3
	s_add_u32 s2, s2, s3
	s_addk_i32 s2, 0x500
	s_lshl_b32 s3, s5, 3
	s_nop 0
	v_writelane_b32 v254, s2, 52
	v_writelane_b32 v254, s3, 50
	s_mov_b32 s88, s5
	s_movk_i32 s99, 0xf7f
	s_mov_b32 s98, 1
	s_waitcnt lgkmcnt(0)
	s_branch .Ltr_entry
.Ls5_entry:
	s_load_dwordx16 s[68:83], s[0:1], 0x40
	s_load_dwordx16 s[12:27], s[0:1], 0x80
	s_load_dwordx16 s[36:51], s[0:1], 0x158
	v_readlane_b32 s2, v255, 6
	v_readlane_b32 s3, v255, 7
	v_readlane_b32 s4, v253, 40
	s_nop 1
	v_writelane_b32 v253, s2, 42
	v_writelane_b32 v253, s3, 43
	s_sub_u32 s84, s84, s4
	v_lshlrev_b32_e32 v2, 2, v152
	v_lshl_add_u32 v162, s84, 9, v154
	v_mov_b32_e32 v163, 0
	s_waitcnt lgkmcnt(0)
	s_branch .Ls5_go
.Ls5_ret:
	v_readlane_b32 s2, v253, 42
	v_readlane_b32 s3, v253, 43
	v_readlane_b32 s84, v253, 44
	s_nop 1
	v_writelane_b32 v255, s2, 6
	v_writelane_b32 v255, s3, 7
	s_nop 2
	v_lshl_add_u32 v162, s84, 9, v154
	v_mov_b32_e32 v163, 0
.Ltr_return:
	v_writelane_b32 v254, s96, 50
	v_writelane_b32 v254, s97, 52
	s_mov_b32 s98, 0
	v_mov_b32_e32 v1, v200
	v_mov_b32_e32 v2, v201
	v_mov_b32_e32 v3, v202
	v_mov_b32_e32 v4, v203
	v_mov_b32_e32 v5, v204
	v_mov_b32_e32 v6, v205
	v_mov_b32_e32 v7, v206
	v_mov_b32_e32 v8, v207
	v_mov_b32_e32 v9, v208
	v_mov_b32_e32 v10, v209
	v_mov_b32_e32 v11, v210
	v_mov_b32_e32 v14, v211
	v_mov_b32_e32 v15, v212
	v_mov_b32_e32 v19, v213
	v_mov_b32_e32 v70, v214
	v_mov_b32_e32 v71, v215
	v_mov_b32_e32 v75, v216
	v_mov_b32_e32 v80, v217
	v_mov_b32_e32 v81, v218
	v_mov_b32_e32 v82, v219
	v_mov_b32_e32 v83, v220
	v_readlane_b32 s26, v253, 0
	v_readlane_b32 s27, v253, 1
	v_readlane_b32 s34, v253, 2
	v_readlane_b32 s36, v253, 3
	v_readlane_b32 s37, v253, 4
	v_readlane_b32 s38, v253, 5
	v_readlane_b32 s39, v253, 6
	v_readlane_b32 s40, v253, 7
	v_readlane_b32 s41, v253, 8
	v_readlane_b32 s42, v253, 9
	v_readlane_b32 s43, v253, 10
	v_readlane_b32 s44, v253, 11
	v_readlane_b32 s45, v253, 12
	v_readlane_b32 s46, v253, 13
	v_readlane_b32 s47, v253, 14
	v_readlane_b32 s48, v253, 15
	v_readlane_b32 s49, v253, 16
	v_readlane_b32 s50, v253, 17
	v_readlane_b32 s51, v253, 18
	v_readlane_b32 s53, v253, 19
	v_readlane_b32 s88, v253, 20
	v_readlane_b32 s12, v253, 21
	v_readlane_b32 s13, v253, 22
	v_readlane_b32 s14, v253, 23
	v_readlane_b32 s15, v253, 24
	v_readlane_b32 s16, v253, 25
	v_readlane_b32 s17, v253, 26
	v_readlane_b32 s18, v253, 27
	v_readlane_b32 s19, v253, 28
	v_readlane_b32 s20, v253, 29
	v_readlane_b32 s21, v253, 30
	v_readlane_b32 s22, v253, 31
	v_readlane_b32 s23, v253, 32
	s_nop 4

; DI void hgrn_b2(const Prm& p, int gtid, int GT) {
;     for (int idx = gtid; idx < 64 * 4096; idx += GT) {
;         const int bhx = idx >> 12, e = idx & 4095, v = e >> 5, d4 = (e & 31) * 4; const bool smp = bhx >= 32;
;         float S[4] = {0.f, 0.f, 0.f, 0.f};
;         if (smp) {
; #pragma unroll
;             for (int j = 0; j < 4; ++j) S[j] = p.state_hgrn[((size_t)(bhx - 32) * 128 + d4 + j) * 128 + v];
;             hgrn_b2_steps<1>(p, 2080 + (bhx - 32), v, d4, S); }
;         else { for (int c0 = 0; c0 < 65; c0 += 13) hgrn_b2_steps<13>(p, bhx * 65 + c0, v, d4, S); }
;         float* dst = p.out + (smp ? O_HGS + (size_t)(bhx - 32) * 16384 : O_HGP + (size_t)bhx * 16384);
; #pragma unroll
;         for (int j = 0; j < 4; ++j) dst[(d4 + j) * 128 + v] = S[j];
;     }
.LBB0_876:
	s_or_b64 exec, exec, s[2:3]
	s_mov_b64 s[2:3], 0
	s_and_saveexec_b64 s[0:1], s[10:11]
	s_xor_b64 s[0:1], exec, s[0:1]
	s_cbranch_execnz .LBB0_853
	s_branch .LBB0_878
.Ltr_tramp_a:
	s_branch .Ltr_entry
.Ltr_tramp_b:
	s_branch .Ltr_return2
.LBB0_877:
	s_mov_b64 s[2:3], -1
	s_and_saveexec_b64 s[0:1], s[10:11]
	s_xor_b64 s[0:1], exec, s[0:1]
	s_cbranch_execnz .LBB0_853

;     __host__ __device__ bool next(int i, Unit& u) const {
;         const long L = (long)i * G + c; if (L >= nwg) return false;
;         map((int)L, u); return true;
; __global__ void __launch_bounds__(512, 2) fwd_megakernel(Prm p) {
;     ...
;     { EpiUp E; E.SSQ = p.SSQ; E.RINV = p.RINV; E.H = p.H; run_gemm(lds, p.XB, p.Wup0, 4096, 1024, E); }
.LBB0_1519:
	s_movk_i32 s4, 2096

; DI void phase_prologue(const Prm& p, LAS unsigned char* lds, int tid, int lane, int wave) {
;     ...
;     for (int it = gw; it < NITEMS; it += NGW) {
;         int r = it;
;         if (r < I1) { transpose_item(p.w_in_even, 2560, p.Wt1, 1024, p.ln_mix, scr, r, lane); continue; } r -= I1;
;         if (r < I2) { transpose_item(p.w_glu, 512, p.Wglu, 512, nullptr, scr, r, lane); continue; } r -= I2;
;         if (r < I3) { transpose_item(p.w_out_even, 1024, p.Wo0, 1024, nullptr, scr, r, lane); continue; } r -= I3;
;         if (r < I4) { transpose_item(p.w_up, 4096, p.Wup0, 1024, p.ln_mlp, scr, r, lane); continue; } r -= I4;
;         if (r < I5) { transpose_item(p.w_down, 1024, p.Wdn0, 4096, nullptr, scr, r, lane); continue; } r -= I5;
;         if (r < I6) { transpose_item(p.w_in_odd, 3072, p.Wqkv, 1024, p.ln_mix + 1024, scr, r, lane); continue; } r -= I6;
;         if (r < I3) { transpose_item(p.w_out_odd, 1024, p.Wo1, 1024, nullptr, scr, r, lane); continue; } r -= I3;
;         if (r < I4) { transpose_item(p.w_up + (size_t)1024 * 4096, 4096, p.Wup1, 1024, p.ln_mlp + 1024, scr, r, lane); continue; } r -= I4;
;         transpose_item(p.w_down + (size_t)4096 * 1024, 1024, p.Wdn1, 4096, nullptr, scr, r, lane);
;     }
; __global__ void __launch_bounds__(512, 2) fwd_megakernel(Prm p) {
;     ...
;     { EpiUp E; E.SSQ = p.SSQ; E.RINV = p.RINV; E.H = p.H; run_gemm(lds, p.XB, p.Wup0, 4096, 1024, E); }
.Ltr2_mod_done:
	s_cmp_lt_u32 s84, s4
	s_cbranch_scc1 .Ltr2_skip
	s_sub_u32 s5, s88, s4
	v_mov_b32_e32 v200, v3
	v_mov_b32_e32 v201, v60
	v_mov_b32_e32 v202, v61
	v_mov_b32_e32 v203, v62
	v_mov_b32_e32 v204, v63
	v_mov_b32_e32 v205, v64
	v_mov_b32_e32 v206, v65
	v_mov_b32_e32 v207, v66
	v_mov_b32_e32 v208, v67
	v_mov_b32_e32 v209, v68
	v_mov_b32_e32 v210, v69
	v_mov_b32_e32 v211, v70
	v_mov_b32_e32 v212, v71
	v_mov_b32_e32 v213, v72
	v_mov_b32_e32 v214, v73
	v_mov_b32_e32 v215, v74
	v_mov_b32_e32 v216, v75
	v_mov_b32_e32 v217, v76
	v_mov_b32_e32 v218, v77
	v_mov_b32_e32 v219, v78
	v_mov_b32_e32 v220, v79
	v_mov_b32_e32 v221, v80
	v_mov_b32_e32 v222, v81
	v_mov_b32_e32 v223, v82
	v_mov_b32_e32 v224, v83
	v_writelane_b32 v253, s26, 0
	v_writelane_b32 v253, s27, 1
	v_writelane_b32 v253, s36, 2
	v_writelane_b32 v253, s37, 3
	v_writelane_b32 v253, s38, 4
	v_writelane_b32 v253, s39, 5
	v_writelane_b32 v253, s42, 6
	v_writelane_b32 v253, s43, 7
	v_writelane_b32 v253, s44, 8
	v_writelane_b32 v253, s45, 9
	v_writelane_b32 v253, s46, 10
	v_writelane_b32 v253, s47, 11
	v_writelane_b32 v253, s50, 12
	v_writelane_b32 v253, s51, 13
	v_writelane_b32 v253, s53, 14
	v_writelane_b32 v253, s60, 15
	v_writelane_b32 v253, s61, 16
	v_writelane_b32 v253, s68, 17
	v_writelane_b32 v253, s69, 18
	v_writelane_b32 v253, s70, 19
	v_writelane_b32 v253, s71, 20
	v_writelane_b32 v253, s72, 21
	v_writelane_b32 v253, s73, 22
	v_writelane_b32 v253, s74, 23
	v_writelane_b32 v253, s75, 24
	v_writelane_b32 v253, s88, 25
	s_mov_b64 s[0:1], s[100:101]
	s_load_dwordx8 s[68:75], s[0:1], 0x40
	s_load_dwordx4 s[24:27], s[0:1], 0xb0
	v_readlane_b32 s2, v254, 50
	s_nop 1
	v_writelane_b32 v253, s2, 30
	v_readlane_b32 s2, v254, 52
	s_nop 1
	v_writelane_b32 v253, s2, 31
	v_readlane_b32 s3, v254, 49
	s_sub_u32 s2, s84, s4
	s_lshl_b32 s2, s2, 3
	s_add_u32 s2, s2, s3
	s_addk_i32 s2, 0xf80
	s_lshl_b32 s3, s5, 3
	s_nop 0
	v_writelane_b32 v254, s2, 52
	v_writelane_b32 v254, s3, 50
	s_mov_b32 s88, s5
	v_lshlrev_b32_e32 v161, 4, v154
	s_movk_i32 s99, 0x2f7f
	s_mov_b32 s98, 2
	s_waitcnt lgkmcnt(0)
	s_branch .Ltr_tramp_a
.Ltr_return2:
	v_readlane_b32 s2, v253, 30
	s_nop 1
	v_writelane_b32 v254, s2, 50
	v_readlane_b32 s2, v253, 31
	s_nop 1
	v_writelane_b32 v254, s2, 52
	s_mov_b32 s98, 0
	v_mov_b32_e32 v3, v200
	v_mov_b32_e32 v60, v201
	v_mov_b32_e32 v61, v202
	v_mov_b32_e32 v62, v203
	v_mov_b32_e32 v63, v204
	v_mov_b32_e32 v64, v205
	v_mov_b32_e32 v65, v206
	v_mov_b32_e32 v66, v207
	v_mov_b32_e32 v67, v208
	v_mov_b32_e32 v68, v209
	v_mov_b32_e32 v69, v210
	v_mov_b32_e32 v70, v211
	v_mov_b32_e32 v71, v212
	v_mov_b32_e32 v72, v213
	v_mov_b32_e32 v73, v214
	v_mov_b32_e32 v74, v215
	v_mov_b32_e32 v75, v216
	v_mov_b32_e32 v76, v217
	v_mov_b32_e32 v77, v218
	v_mov_b32_e32 v78, v219
	v_mov_b32_e32 v79, v220
	v_mov_b32_e32 v80, v221
	v_mov_b32_e32 v81, v222
	v_mov_b32_e32 v82, v223
	v_mov_b32_e32 v83, v224
	v_readlane_b32 s26, v253, 0
	v_readlane_b32 s27, v253, 1
	v_readlane_b32 s36, v253, 2
	v_readlane_b32 s37, v253, 3
	v_readlane_b32 s38, v253, 4
	v_readlane_b32 s39, v253, 5
	v_readlane_b32 s42, v253, 6
	v_readlane_b32 s43, v253, 7
	v_readlane_b32 s44, v253, 8
	v_readlane_b32 s45, v253, 9
	v_readlane_b32 s46, v253, 10
	v_readlane_b32 s47, v253, 11
	v_readlane_b32 s50, v253, 12
	v_readlane_b32 s51, v253, 13
	v_readlane_b32 s53, v253, 14
	v_readlane_b32 s60, v253, 15
	v_readlane_b32 s61, v253, 16
	v_readlane_b32 s68, v253, 17
	v_readlane_b32 s69, v253, 18
	v_readlane_b32 s70, v253, 19
	v_readlane_b32 s71, v253, 20
	v_readlane_b32 s72, v253, 21
	v_readlane_b32 s73, v253, 22
	v_readlane_b32 s74, v253, 23
	v_readlane_b32 s75, v253, 24
	v_readlane_b32 s88, v253, 25
	s_nop 4
